# phase-0 pe-bias dot products spread one per workgroup instead of eight on each of the first 32 workgroups
# speedup vs baseline: 1.0640x; 1.0124x over previous
; DI int tidx() { int t = threadIdx.x; asm volatile("" : "+v"(t)); return t; }
; DI int bidx() { int b = blockIdx.x; asm volatile("" : "+s"(b)); return b; }
; DI const float* IN(int i) { return *(const float* const __attribute__((address_space(4)))*)(KA() + 8 * i); }
; DI char* WS(const Params&) { return *(char* const __attribute__((address_space(4)))*)(KA() + 8 * 30); }
; DI void phase0(const Params& p, int l, char* smraw) {
;     ...
;     const int lane = tidx() & 63, gw = bidx() * 8 + (tidx() >> 6), nw = gridDim.x * 8;
;     float* peb = (float*)(WS(p) + O_PEB);
;     for (int o = gw; o < 256; o += nw) {
;       const int which = o >> 7, n = o & 127;
;       const float* pe = (which ? IN(7) : IN(4)) + (size_t)l * 2048;
;       const float* w1 = (which ? IN(8) : IN(5)) + (size_t)l * 2048 * 128;
;       float s = 0.f;
;       float pa[32], pb[32];
; #pragma unroll
;       for (int i = 0; i < 32; ++i) { const int k = lane + 64 * i; pa[i] = pe[k]; pb[i] = w1[(size_t)k * 128 + n]; }
; #pragma unroll
;       for (int i = 0; i < 32; ++i) s += pa[i] * pb[i];
;       s = wave_sum(s);
;       if (lane == 0) peb[o] = s;
.LBB0_164:
	s_or_b64 exec, exec, s[2:3]
	v_mov_b32_e32 v0, v201
	v_readlane_b32 s0, v252, 4
	v_mov_b32_e32 v2, v201
	v_readlane_b32 s6, v252, 6
	v_ashrrev_i32_e32 v2, 6, v2
	v_lshl_add_u32 v2, v2, 8, s0
	s_movk_i32 s0, 0x100
	v_readlane_b32 s7, v252, 7
	v_cmp_gt_i32_e32 vcc, s0, v2
	s_and_saveexec_b64 s[2:3], vcc
	s_cbranch_execz .LBB0_177
	s_load_dwordx2 s[36:37], s[6:7], 0xf0
	v_readlane_b32 s0, v252, 52
	v_readlane_b32 s1, v252, 53
	s_lshl_b32 s0, s68, 11
	s_mov_b32 s4, s10
	v_and_b32_e32 v0, 63, v0
	v_writelane_b32 v252, s0, 52
	v_ashrrev_i32_e32 v3, 31, v2
	s_lshl_b64 s[34:35], s[0:1], 9
	v_writelane_b32 v252, s1, 53
	v_lshlrev_b32_e32 v4, 9, v0
	v_or_b32_e32 v72, 0x400, v0
	v_or_b32_e32 v74, 0x440, v0
	v_or_b32_e32 v76, 0x480, v0
	v_or_b32_e32 v78, 0x4c0, v0
	v_or_b32_e32 v80, 0x500, v0
	v_or_b32_e32 v82, 0x540, v0
	v_or_b32_e32 v84, 0x580, v0
	v_or_b32_e32 v86, 0x5c0, v0
	v_or_b32_e32 v88, 0x600, v0
	v_or_b32_e32 v90, 0x640, v0
	v_or_b32_e32 v92, 0x680, v0
	v_or_b32_e32 v94, 0x6c0, v0
	v_or_b32_e32 v96, 0x700, v0
	v_or_b32_e32 v98, 0x740, v0
	v_or_b32_e32 v100, 0x780, v0
	v_or_b32_e32 v102, 0x7c0, v0
	s_waitcnt lgkmcnt(0)
	v_lshl_add_u64 v[68:69], v[2:3], 2, s[36:37]
	s_mov_b64 s[0:1], 0x1288000
	s_ashr_i32 s5, s4, 31
	v_cmp_eq_u32_e32 vcc, 0, v0
	v_mov_b32_e32 v5, v1
	v_or_b32_e32 v6, 0x8000, v4
	v_mov_b32_e32 v7, v1
	v_or_b32_e32 v8, 0x10000, v4
	v_mov_b32_e32 v9, v1
	v_or_b32_e32 v10, 0x18000, v4
	v_mov_b32_e32 v11, v1
	v_or_b32_e32 v12, 0x20000, v4
	v_mov_b32_e32 v13, v1
	v_or_b32_e32 v14, 0x28000, v4
	v_mov_b32_e32 v15, v1
	v_or_b32_e32 v16, 0x30000, v4
	v_mov_b32_e32 v17, v1
	v_or_b32_e32 v18, 0x38000, v4
	v_mov_b32_e32 v19, v1
	v_or_b32_e32 v20, 0x40000, v4
	v_mov_b32_e32 v21, v1
	v_or_b32_e32 v22, 0x48000, v4
	v_mov_b32_e32 v23, v1
	v_or_b32_e32 v24, 0x50000, v4
	v_mov_b32_e32 v25, v1
	v_or_b32_e32 v26, 0x58000, v4
	v_mov_b32_e32 v27, v1
	v_or_b32_e32 v28, 0x60000, v4
	v_mov_b32_e32 v29, v1
	v_or_b32_e32 v30, 0x68000, v4
	v_mov_b32_e32 v31, v1
	v_or_b32_e32 v32, 0x70000, v4
	v_mov_b32_e32 v33, v1
	v_or_b32_e32 v34, 0x78000, v4
	v_mov_b32_e32 v35, v1
	v_lshlrev_b32_e32 v36, 9, v72
	v_mov_b32_e32 v37, v1
	v_lshlrev_b32_e32 v38, 9, v74
	v_mov_b32_e32 v39, v1
	v_lshlrev_b32_e32 v40, 9, v76
	v_mov_b32_e32 v41, v1
	v_lshlrev_b32_e32 v42, 9, v78
	v_mov_b32_e32 v43, v1
	v_lshlrev_b32_e32 v44, 9, v80
	v_mov_b32_e32 v45, v1
	v_lshlrev_b32_e32 v46, 9, v82
	v_mov_b32_e32 v47, v1
	v_lshlrev_b32_e32 v48, 9, v84
	v_mov_b32_e32 v49, v1
	v_lshlrev_b32_e32 v50, 9, v86
	v_mov_b32_e32 v51, v1
	v_lshlrev_b32_e32 v52, 9, v88
	v_mov_b32_e32 v53, v1
	v_lshlrev_b32_e32 v54, 9, v90
	v_mov_b32_e32 v55, v1
	v_lshlrev_b32_e32 v56, 9, v92
	v_mov_b32_e32 v57, v1
	v_lshlrev_b32_e32 v58, 9, v94
	v_mov_b32_e32 v59, v1
	v_lshlrev_b32_e32 v60, 9, v96
	v_mov_b32_e32 v61, v1
	v_lshlrev_b32_e32 v62, 9, v98
	v_mov_b32_e32 v63, v1
	v_lshlrev_b32_e32 v64, 9, v100
	v_mov_b32_e32 v65, v1
	v_lshlrev_b32_e32 v66, 9, v102
	v_mov_b32_e32 v67, v1
	v_lshl_add_u64 v[68:69], v[68:69], 0, s[0:1]
	s_lshl_b64 s[38:39], s[4:5], 2
	s_mov_b64 s[40:41], 0
	v_lshlrev_b32_e32 v70, 2, v0
	v_lshlrev_b32_e32 v72, 2, v72
	v_lshlrev_b32_e32 v74, 2, v74
	v_lshlrev_b32_e32 v76, 2, v76
	v_lshlrev_b32_e32 v78, 2, v78
	v_lshlrev_b32_e32 v80, 2, v80
	v_lshlrev_b32_e32 v82, 2, v82
	v_lshlrev_b32_e32 v84, 2, v84
	v_lshlrev_b32_e32 v86, 2, v86
	v_lshlrev_b32_e32 v88, 2, v88
	v_lshlrev_b32_e32 v90, 2, v90
	v_lshlrev_b32_e32 v92, 2, v92
	v_lshlrev_b32_e32 v94, 2, v94
	v_lshlrev_b32_e32 v96, 2, v96
	v_lshlrev_b32_e32 v98, 2, v98
	v_lshlrev_b32_e32 v100, 2, v100
	v_lshlrev_b32_e32 v102, 2, v102
	s_branch .LBB0_167
